# attention epilogues: v_permlane32_swap pairs so each lane stores 16 contiguous bytes (dwordx4) - doc 7.3
# speedup vs baseline: 1.0095x; 1.0095x over previous
; __device__ __forceinline__ unsigned pk_bf16(float lo, float hi) { return pg8::cvt_pk_bf16(lo, hi); }
; template <int DV, int NMAP>
; __device__ __forceinline__ void attn_unit(LAS unsigned char* lds, const bf16_t* U, bf16_t* MIX, const float* logf, int b, int h, int qb, float lam, float slope2, const float* gn, float outscale, const int tid) {
;     ...
;     __syncthreads();
;     const float inv = 1.0f / (l_run + __shfl_xor(l_run, 32));
;     const size_t orow = (rowbase + qrow0 + r32) * DM;
;     if (NMAP == 1) {
; #pragma unroll
;         for (int d = 0; d < NDB; ++d)
; #pragma unroll
;             for (int g = 0; g < 4; ++g) { u32x2 w; w.x = pk_bf16(o[d][4 * g] * inv, o[d][4 * g + 1] * inv); w.y = pk_bf16(o[d][4 * g + 2] * inv, o[d][4 * g + 3] * inv);
;                 *(u32x2*)(MIX + orow + 64 * h + 32 * d + 8 * g + 4 * hi) = w; }
;         __syncthreads();
.LBB0_205:
	ds_bpermute_b32 v0, v224, v105
	s_lshl_b32 s20, s33, 1
	s_waitcnt lgkmcnt(0)
	s_barrier
	v_add_f32_e32 v0, v105, v0
	v_div_scale_f32 v34, s[30:31], v0, v0, 1.0
	v_rcp_f32_e32 v35, v34
	v_div_scale_f32 v36, vcc, 1.0, v0, 1.0
	v_readlane_b32 s30, v250, 34
	v_fma_f32 v37, -v34, v35, 1.0
	v_fmac_f32_e32 v35, v37, v35
	v_mul_f32_e32 v37, v36, v35
	v_fma_f32 v38, -v34, v37, v36
	v_fmac_f32_e32 v37, v38, v35
	v_fma_f32 v34, -v34, v37, v36
	v_div_fmas_f32 v34, v34, v35, v37
	v_readlane_b32 s31, v250, 35
	s_add_u32 s30, s30, s20
	v_div_fixup_f32 v36, v34, v0, 1.0
	s_addc_u32 s31, s31, 0
	v_lshlrev_b64 v[34:35], 11, v[98:99]
	v_lshl_add_u64 v[34:35], s[30:31], 0, v[34:35]
	v_lshlrev_b32_e32 v0, 1, v130
	v_lshl_add_u64 v[34:35], v[34:35], 0, v[0:1]
	v_lshl_add_u64 v[34:35], v[34:35], 0, v[0:1]
	v_mul_f32_e32 v56, v2, v36
	v_mul_f32_e32 v57, v3, v36
	v_cvt_pk_bf16_f32 v40, v56, v57
	v_mul_f32_e32 v56, v4, v36
	v_mul_f32_e32 v57, v5, v36
	v_cvt_pk_bf16_f32 v41, v56, v57
	v_mul_f32_e32 v56, v6, v36
	v_mul_f32_e32 v57, v7, v36
	v_cvt_pk_bf16_f32 v42, v56, v57
	v_mul_f32_e32 v56, v8, v36
	v_mul_f32_e32 v57, v9, v36
	v_cvt_pk_bf16_f32 v43, v56, v57
	s_nop 1
	v_permlane32_swap_b32_e32 v40, v42
	v_permlane32_swap_b32_e32 v41, v43
	global_store_dwordx4 v[34:35], v[40:43], off
	v_mul_f32_e32 v56, v10, v36
	v_mul_f32_e32 v57, v11, v36
	v_cvt_pk_bf16_f32 v44, v56, v57
	v_mul_f32_e32 v56, v12, v36
	v_mul_f32_e32 v57, v13, v36
	v_cvt_pk_bf16_f32 v45, v56, v57
	v_mul_f32_e32 v56, v14, v36
	v_mul_f32_e32 v57, v15, v36
	v_cvt_pk_bf16_f32 v46, v56, v57
	v_mul_f32_e32 v56, v16, v36
	v_mul_f32_e32 v57, v17, v36
	v_cvt_pk_bf16_f32 v47, v56, v57
	s_nop 1
	v_permlane32_swap_b32_e32 v44, v46
	v_permlane32_swap_b32_e32 v45, v47
	global_store_dwordx4 v[34:35], v[44:47], off offset:32
	v_mul_f32_e32 v56, v18, v36
	v_mul_f32_e32 v57, v19, v36
	v_cvt_pk_bf16_f32 v48, v56, v57
	v_mul_f32_e32 v56, v20, v36
	v_mul_f32_e32 v57, v21, v36
	v_cvt_pk_bf16_f32 v49, v56, v57
	v_mul_f32_e32 v56, v22, v36
	v_mul_f32_e32 v57, v23, v36
	v_cvt_pk_bf16_f32 v50, v56, v57
	v_mul_f32_e32 v56, v24, v36
	v_mul_f32_e32 v57, v25, v36
	v_cvt_pk_bf16_f32 v51, v56, v57
	s_nop 1
	v_permlane32_swap_b32_e32 v48, v50
	v_permlane32_swap_b32_e32 v49, v51
	global_store_dwordx4 v[34:35], v[48:51], off offset:64
	v_mul_f32_e32 v56, v26, v36
	v_mul_f32_e32 v57, v27, v36
	v_cvt_pk_bf16_f32 v52, v56, v57
	v_mul_f32_e32 v56, v28, v36
	v_mul_f32_e32 v57, v29, v36
	v_cvt_pk_bf16_f32 v53, v56, v57
	v_mul_f32_e32 v56, v30, v36
	v_mul_f32_e32 v57, v31, v36
	v_cvt_pk_bf16_f32 v54, v56, v57
	v_mul_f32_e32 v56, v32, v36
	v_mul_f32_e32 v57, v33, v36
	v_cvt_pk_bf16_f32 v55, v56, v57
	s_nop 1
	v_permlane32_swap_b32_e32 v52, v54
	v_permlane32_swap_b32_e32 v53, v55
	global_store_dwordx4 v[34:35], v[52:55], off offset:96
	s_mov_b64 s[30:31], 0
	s_barrier

; template <int DV, int NMAP>
; __device__ __forceinline__ void attn_unit(LAS unsigned char* lds, const bf16_t* U, bf16_t* MIX, const float* logf, int b, int h, int qb, float lam, float slope2, const float* gn, float outscale, const int tid) {
;     ...
;         __syncthreads();
;         if (map == 0) {
;             float ss = 0.f;
; #pragma unroll
;             for (int d = 0; d < NDB; ++d)
; #pragma unroll
;                 for (int r = 0; r < 16; ++r) { const float v = o[d][r] * inv - ex[(d * 16 + r) * 64]; o[d][r] = v; ss += v * v; }
;             ss += __shfl_xor(ss, 32);
.LBB0_231:
	s_cmpk_gt_u32 s33, 0xff
	s_waitcnt lgkmcnt(0)
	s_barrier
	s_cbranch_scc1 .LBB0_175
	global_load_dwordx4 v[80:83], v[132:133], off
	global_load_dwordx4 v[84:87], v[132:133], off offset:32
	global_load_dwordx4 v[88:91], v[132:133], off offset:64
	global_load_dwordx4 v[92:95], v[132:133], off offset:96
	global_load_dwordx4 v[96:99], v[132:133], off offset:128
	global_load_dwordx4 v[100:103], v[132:133], off offset:160
	global_load_dwordx4 v[104:107], v[132:133], off offset:192
	global_load_dwordx4 v[108:111], v[132:133], off offset:224
	global_load_dwordx4 v[112:115], v[132:133], off offset:256
	global_load_dwordx4 v[116:119], v[132:133], off offset:288
	global_load_dwordx4 v[152:155], v[132:133], off offset:320
	global_load_dwordx4 v[156:159], v[132:133], off offset:352
	global_load_dwordx4 v[160:163], v[132:133], off offset:384
	global_load_dwordx4 v[164:167], v[132:133], off offset:416
	global_load_dwordx4 v[168:171], v[132:133], off offset:448
	global_load_dwordx4 v[172:175], v[132:133], off offset:480
	ds_read2st64_b32 v[66:67], v77 offset0:33 offset1:34
	ds_read2st64_b32 v[68:69], v77 offset0:35 offset1:36
	ds_read2st64_b32 v[70:71], v77 offset0:53 offset1:54
	s_lshl_b32 s20, s27, 1
	s_waitcnt lgkmcnt(2)
	v_fma_f32 v66, v50, v0, -v66
	v_fma_f32 v50, v51, v0, -v67
	s_waitcnt lgkmcnt(1)
	v_fma_f32 v51, v52, v0, -v68
	v_fma_f32 v52, v53, v0, -v69
	ds_read2st64_b32 v[68:69], v77 offset0:37 offset1:38
	v_mul_f32_e32 v78, v50, v50
	v_fmac_f32_e32 v78, v66, v66
	v_fmac_f32_e32 v78, v51, v51
	v_fmac_f32_e32 v78, v52, v52
	s_waitcnt lgkmcnt(0)
	v_fma_f32 v53, v54, v0, -v68
	v_fma_f32 v54, v55, v0, -v69
	ds_read2st64_b32 v[68:69], v77 offset0:39 offset1:40
	v_fmac_f32_e32 v78, v53, v53
	v_fmac_f32_e32 v78, v54, v54
	s_waitcnt lgkmcnt(0)
	v_fma_f32 v55, v56, v0, -v68
	v_fma_f32 v56, v57, v0, -v69
	ds_read2st64_b32 v[68:69], v77 offset0:41 offset1:42
	v_fmac_f32_e32 v78, v55, v55
	v_fmac_f32_e32 v78, v56, v56
	s_waitcnt lgkmcnt(0)
	v_fma_f32 v58, v58, v0, -v68
	v_fma_f32 v57, v59, v0, -v69
	ds_read2st64_b32 v[68:69], v77 offset0:43 offset1:44
	v_fmac_f32_e32 v78, v58, v58
	v_fmac_f32_e32 v78, v57, v57
	s_waitcnt lgkmcnt(0)
	v_fma_f32 v67, v60, v0, -v68
	v_fma_f32 v60, v61, v0, -v69
	ds_read2st64_b32 v[68:69], v77 offset0:45 offset1:46
	v_fmac_f32_e32 v78, v67, v67
	v_fmac_f32_e32 v78, v60, v60
	s_waitcnt lgkmcnt(0)
	v_fma_f32 v61, v62, v0, -v68
	v_fma_f32 v59, v63, v0, -v69
	ds_read2st64_b32 v[62:63], v77 offset0:47 offset1:48
	v_fmac_f32_e32 v78, v61, v61
	v_fmac_f32_e32 v78, v59, v59
	s_waitcnt lgkmcnt(0)
	v_fma_f32 v68, v64, v0, -v62
	v_fma_f32 v63, v65, v0, -v63
	ds_read2st64_b32 v[64:65], v77 offset0:49 offset1:50
	v_fmac_f32_e32 v78, v68, v68
	v_fmac_f32_e32 v78, v63, v63
	s_waitcnt lgkmcnt(0)
	v_fma_f32 v62, v34, v0, -v64
	v_fma_f32 v34, v35, v0, -v65
	ds_read2st64_b32 v[64:65], v77 offset0:51 offset1:52
	v_fma_f32 v35, v39, v0, -v71
	v_fmac_f32_e32 v78, v62, v62
	v_fmac_f32_e32 v78, v34, v34
	s_waitcnt lgkmcnt(0)
	v_fma_f32 v64, v36, v0, -v64
	v_fma_f32 v36, v37, v0, -v65
	v_fma_f32 v37, v38, v0, -v70
	ds_read2st64_b32 v[38:39], v77 offset0:55 offset1:56
	v_fmac_f32_e32 v78, v64, v64
	v_fmac_f32_e32 v78, v36, v36
	v_fmac_f32_e32 v78, v37, v37
	v_fmac_f32_e32 v78, v35, v35
	s_waitcnt lgkmcnt(0)
	v_fma_f32 v69, v40, v0, -v38
	v_fma_f32 v65, v41, v0, -v39
	ds_read2st64_b32 v[40:41], v77 offset0:57 offset1:58
	v_fmac_f32_e32 v78, v69, v69
	v_fmac_f32_e32 v78, v65, v65
	s_waitcnt lgkmcnt(0)
	v_fma_f32 v39, v42, v0, -v40
	v_fma_f32 v38, v43, v0, -v41
	ds_read2st64_b32 v[40:41], v77 offset0:59 offset1:60
	v_fmac_f32_e32 v78, v39, v39
	v_fmac_f32_e32 v78, v38, v38
	s_waitcnt lgkmcnt(0)
	v_fma_f32 v43, v44, v0, -v40
	v_fma_f32 v41, v45, v0, -v41
	ds_read2st64_b32 v[44:45], v77 offset0:61 offset1:62
	v_fmac_f32_e32 v78, v43, v43
	v_fmac_f32_e32 v78, v41, v41
	s_waitcnt lgkmcnt(0)
	v_fma_f32 v42, v46, v0, -v44
	v_fma_f32 v40, v47, v0, -v45
	ds_read2st64_b32 v[44:45], v77 offset0:63 offset1:64
	v_fmac_f32_e32 v78, v42, v42
	v_fmac_f32_e32 v78, v40, v40
	s_waitcnt lgkmcnt(0)
	v_fma_f32 v47, v48, v0, -v44
	v_fma_f32 v45, v49, v0, -v45
	ds_read2st64_b32 v[48:49], v77 offset0:65 offset1:66
	v_fmac_f32_e32 v78, v47, v47
	v_fmac_f32_e32 v78, v45, v45
	s_waitcnt lgkmcnt(0)
	v_fma_f32 v44, v18, v0, -v48
	v_fma_f32 v18, v19, v0, -v49
	ds_read2st64_b32 v[48:49], v77 offset0:67 offset1:68
	v_fmac_f32_e32 v78, v44, v44
	v_fmac_f32_e32 v78, v18, v18
	s_waitcnt lgkmcnt(0)
	v_fma_f32 v46, v20, v0, -v48
	v_fma_f32 v20, v21, v0, -v49
	ds_read2st64_b32 v[48:49], v77 offset0:69 offset1:70
	v_fmac_f32_e32 v78, v46, v46
	v_fmac_f32_e32 v78, v20, v20
	s_waitcnt lgkmcnt(0)
	v_fma_f32 v21, v22, v0, -v48
	v_fma_f32 v19, v23, v0, -v49
	ds_read2st64_b32 v[22:23], v77 offset0:71 offset1:72
	v_fmac_f32_e32 v78, v21, v21
	v_fmac_f32_e32 v78, v19, v19
	s_waitcnt lgkmcnt(0)
	v_fma_f32 v49, v24, v0, -v22
	v_fma_f32 v48, v25, v0, -v23
	ds_read2st64_b32 v[24:25], v77 offset0:73 offset1:74
	v_fmac_f32_e32 v78, v49, v49
	v_fmac_f32_e32 v78, v48, v48
	s_waitcnt lgkmcnt(0)
	v_fma_f32 v23, v26, v0, -v24
	v_fma_f32 v22, v27, v0, -v25
	ds_read2st64_b32 v[24:25], v77 offset0:75 offset1:76
	ds_read2st64_b32 v[26:27], v77 offset0:77 offset1:78
	v_fmac_f32_e32 v78, v23, v23
	v_fmac_f32_e32 v78, v22, v22
	s_waitcnt lgkmcnt(1)
	v_fma_f32 v28, v28, v0, -v24
	s_waitcnt lgkmcnt(0)
	v_fma_f32 v26, v30, v0, -v26
	v_fma_f32 v24, v31, v0, -v27
	ds_read2st64_b32 v[30:31], v77 offset0:79 offset1:80
	v_fmac_f32_e32 v78, v28, v28
	v_fma_f32 v25, v29, v0, -v25
	v_fmac_f32_e32 v78, v25, v25
	v_fmac_f32_e32 v78, v26, v26
	s_waitcnt lgkmcnt(0)
; __device__ __forceinline__ unsigned pk_bf16(float lo, float hi) { return pg8::cvt_pk_bf16(lo, hi); }
; template <int DV, int NMAP>
; __device__ __forceinline__ void attn_unit(LAS unsigned char* lds, const bf16_t* U, bf16_t* MIX, const float* logf, int b, int h, int qb, float lam, float slope2, const float* gn, float outscale, const int tid) {
;     ...
;             float ss = 0.f;
; #pragma unroll
;             for (int d = 0; d < NDB; ++d)
; #pragma unroll
;                 for (int r = 0; r < 16; ++r) { const float v = o[d][r] * inv - ex[(d * 16 + r) * 64]; o[d][r] = v; ss += v * v; }
;             ss += __shfl_xor(ss, 32);
;             const float rn = outscale / sqrtf(ss * (1.0f / 128.0f) + EPS);
; #pragma unroll
;             for (int d = 0; d < NDB; ++d)
; #pragma unroll
;                 for (int g = 0; g < 4; ++g) { const f32x4 gv = *(const f32x4*)(gn + 32 * d + 8 * g + 4 * hi);
;                     u32x2 w; w.x = pk_bf16(o[d][4 * g] * rn * gv[0], o[d][4 * g + 1] * rn * gv[1]); w.y = pk_bf16(o[d][4 * g + 2] * rn * gv[2], o[d][4 * g + 3] * rn * gv[3]);
;                     *(u32x2*)(MIX + orow + 512 + 128 * h + 32 * d + 8 * g + 4 * hi) = w; }
	v_fma_f32 v76, v32, v0, -v30
	v_fma_f32 v74, v33, v0, -v31
	ds_read2st64_b32 v[30:31], v77 offset0:81 offset1:82
	v_fmac_f32_e32 v78, v24, v24
	v_fmac_f32_e32 v78, v76, v76
	v_fmac_f32_e32 v78, v74, v74
	s_waitcnt lgkmcnt(0)
	v_fma_f32 v32, v2, v0, -v30
	v_fma_f32 v31, v3, v0, -v31
	ds_read2st64_b32 v[2:3], v77 offset0:83 offset1:84
	v_fmac_f32_e32 v78, v32, v32
	v_fmac_f32_e32 v78, v31, v31
	s_waitcnt lgkmcnt(0)
	v_fma_f32 v75, v4, v0, -v2
	v_fma_f32 v72, v5, v0, -v3
	ds_read2st64_b32 v[2:3], v77 offset0:85 offset1:86
	v_fmac_f32_e32 v78, v75, v75
	v_fmac_f32_e32 v78, v72, v72
	s_waitcnt lgkmcnt(0)
	v_fma_f32 v73, v6, v0, -v2
	v_fma_f32 v70, v7, v0, -v3
	ds_read2st64_b32 v[2:3], v77 offset0:87 offset1:88
	v_fmac_f32_e32 v78, v73, v73
	v_fmac_f32_e32 v78, v70, v70
	s_waitcnt lgkmcnt(0)
	v_fma_f32 v71, v8, v0, -v2
	v_fma_f32 v33, v9, v0, -v3
	ds_read2st64_b32 v[2:3], v77 offset0:89 offset1:90
	v_fmac_f32_e32 v78, v71, v71
	v_fmac_f32_e32 v78, v33, v33
	s_waitcnt lgkmcnt(0)
	v_fma_f32 v30, v10, v0, -v2
	v_fma_f32 v29, v11, v0, -v3
	ds_read2st64_b32 v[2:3], v77 offset0:91 offset1:92
	v_fmac_f32_e32 v78, v30, v30
	v_fmac_f32_e32 v78, v29, v29
	s_waitcnt lgkmcnt(0)
	v_fma_f32 v27, v12, v0, -v2
	v_fma_f32 v13, v13, v0, -v3
	ds_read2st64_b32 v[2:3], v77 offset0:93 offset1:94
	v_fmac_f32_e32 v78, v27, v27
	v_fmac_f32_e32 v78, v13, v13
	s_waitcnt lgkmcnt(0)
	v_pk_fma_f32 v[8:9], v[14:15], v[0:1], v[2:3] op_sel_hi:[1,0,1] neg_lo:[0,0,1] neg_hi:[0,0,1]
	s_nop 0
	v_pk_mul_f32 v[2:3], v[8:9], v[8:9]
	s_nop 0
	v_add_f32_e32 v2, v78, v2
	v_add_f32_e32 v4, v2, v3
	ds_read2st64_b32 v[2:3], v77 offset0:95 offset1:96
	s_waitcnt lgkmcnt(0)
	v_pk_fma_f32 v[6:7], v[16:17], v[0:1], v[2:3] op_sel_hi:[1,0,1] neg_lo:[0,0,1] neg_hi:[0,0,1]
	s_nop 0
	v_pk_mul_f32 v[2:3], v[6:7], v[6:7]
	s_nop 0
	v_add_f32_e32 v0, v4, v2
	v_add_f32_e32 v0, v0, v3
	ds_bpermute_b32 v2, v224, v0
	s_waitcnt lgkmcnt(0)
	v_add_f32_e32 v0, v0, v2
	v_fmamk_f32 v0, v0, 0x3c000000, v225
	v_cmp_gt_f32_e64 s[40:41], s16, v0
	v_mul_f32_e32 v2, 0x4f800000, v0
	s_nop 0
	v_cndmask_b32_e64 v0, v0, v2, s[40:41]
	v_sqrt_f32_e32 v2, v0
	s_nop 0
	v_add_u32_e32 v3, -1, v2
	v_fma_f32 v4, -v3, v2, v0
	v_cmp_ge_f32_e32 vcc, 0, v4
	v_add_u32_e32 v4, 1, v2
	s_nop 0
	v_cndmask_b32_e32 v3, v2, v3, vcc
	v_fma_f32 v2, -v4, v2, v0
	v_cmp_lt_f32_e32 vcc, 0, v2
	s_nop 1
	v_cndmask_b32_e32 v2, v3, v4, vcc
	v_mul_f32_e32 v3, 0x37800000, v2
	v_cndmask_b32_e64 v2, v2, v3, s[40:41]
	v_cmp_class_f32_e32 vcc, v0, v226
	s_nop 1
	v_cndmask_b32_e32 v0, v2, v0, vcc
	v_div_scale_f32 v2, s[30:31], v0, v0, v144
	v_rcp_f32_e32 v3, v2
	v_readlane_b32 s30, v250, 34
	v_readlane_b32 s31, v250, 35
	v_fma_f32 v4, -v2, v3, 1.0
	v_fmac_f32_e32 v3, v4, v3
	v_div_scale_f32 v4, vcc, v144, v0, v144
	v_mul_f32_e32 v5, v4, v3
	v_fma_f32 v10, -v2, v5, v4
	v_fmac_f32_e32 v5, v10, v3
	v_fma_f32 v2, -v2, v5, v4
	v_div_fmas_f32 v2, v2, v3, v5
	v_div_fixup_f32 v12, v2, v0, v144
	v_lshlrev_b32_e32 v0, 11, v147
	v_lshl_add_u64 v[2:3], s[30:31], 0, v[0:1]
	v_lshl_add_u64 v[2:3], v[2:3], 0, s[20:21]
	v_lshlrev_b32_e32 v0, 1, v130
	v_lshl_add_u64 v[10:11], v[2:3], 0, v[0:1]
	v_lshl_add_u64 v[10:11], v[10:11], 0, v[0:1]
	s_waitcnt vmcnt(0)
	v_mov_b32_e32 v2, v80
	v_mov_b32_e32 v3, v81
	v_mov_b32_e32 v4, v82
	v_mov_b32_e32 v5, v83
	v_mul_f32_e32 v0, v66, v12
	v_mul_f32_e32 v0, v2, v0
	v_mul_f32_e32 v2, v50, v12
	v_mul_f32_e32 v2, v3, v2
	v_mul_f32_e32 v3, v52, v12
	v_cvt_pk_bf16_f32 v176, v0, v2
	v_mul_f32_e32 v0, v51, v12
	v_mul_f32_e32 v3, v5, v3
	v_mul_f32_e32 v0, v4, v0
	v_cvt_pk_bf16_f32 v177, v0, v3
	v_mov_b32_e32 v2, v84
	v_mov_b32_e32 v3, v85
	v_mov_b32_e32 v4, v86
	v_mov_b32_e32 v5, v87
	v_mul_f32_e32 v0, v53, v12
	v_mul_f32_e32 v0, v2, v0
	v_mul_f32_e32 v2, v54, v12
	v_mul_f32_e32 v2, v3, v2
	v_mul_f32_e32 v3, v56, v12
	v_cvt_pk_bf16_f32 v178, v0, v2
	v_mul_f32_e32 v0, v55, v12
	v_mul_f32_e32 v3, v5, v3
	v_mul_f32_e32 v0, v4, v0
	v_cvt_pk_bf16_f32 v179, v0, v3
	s_nop 1
	v_permlane32_swap_b32_e32 v176, v178
	v_permlane32_swap_b32_e32 v177, v179
	global_store_dwordx4 v[10:11], v[176:179], off offset:1024
	v_mov_b32_e32 v2, v88
	v_mov_b32_e32 v3, v89
	v_mov_b32_e32 v4, v90
	v_mov_b32_e32 v5, v91
	v_mul_f32_e32 v0, v58, v12
	v_mul_f32_e32 v0, v0, v2
	v_mul_f32_e32 v2, v57, v12
	v_mul_f32_e32 v2, v2, v3
	v_mul_f32_e32 v3, v60, v12
	v_cvt_pk_bf16_f32 v176, v0, v2
	v_mul_f32_e32 v0, v67, v12
	v_mul_f32_e32 v3, v3, v5
	v_mul_f32_e32 v0, v0, v4
	v_cvt_pk_bf16_f32 v177, v0, v3
	v_mov_b32_e32 v2, v92
	v_mov_b32_e32 v3, v93
	v_mov_b32_e32 v4, v94
	v_mov_b32_e32 v5, v95
	v_mul_f32_e32 v0, v61, v12
	v_mul_f32_e32 v0, v0, v2
	v_mul_f32_e32 v2, v59, v12
	v_mul_f32_e32 v2, v2, v3
	v_mul_f32_e32 v3, v63, v12
	v_cvt_pk_bf16_f32 v178, v0, v2
	v_mul_f32_e32 v0, v68, v12
	v_mul_f32_e32 v3, v3, v5
	v_mul_f32_e32 v0, v0, v4
	v_cvt_pk_bf16_f32 v179, v0, v3
	s_nop 1
	v_permlane32_swap_b32_e32 v176, v178
	v_permlane32_swap_b32_e32 v177, v179
	global_store_dwordx4 v[10:11], v[176:179], off offset:1056
	v_mov_b32_e32 v2, v96
	v_mov_b32_e32 v3, v97
	v_mov_b32_e32 v4, v98
	v_mov_b32_e32 v5, v99
	v_mul_f32_e32 v0, v62, v12
	v_mul_f32_e32 v0, v0, v2
	v_mul_f32_e32 v2, v34, v12
	v_mul_f32_e32 v2, v2, v3
	v_mul_f32_e32 v3, v36, v12
; __device__ __forceinline__ unsigned pk_bf16(float lo, float hi) { return pg8::cvt_pk_bf16(lo, hi); }
; template <int DV, int NMAP>
; __device__ __forceinline__ void attn_unit(LAS unsigned char* lds, const bf16_t* U, bf16_t* MIX, const float* logf, int b, int h, int qb, float lam, float slope2, const float* gn, float outscale, const int tid) {
;     ...
; #pragma unroll
;             for (int d = 0; d < NDB; ++d)
; #pragma unroll
;                 for (int g = 0; g < 4; ++g) { const f32x4 gv = *(const f32x4*)(gn + 32 * d + 8 * g + 4 * hi);
;                     u32x2 w; w.x = pk_bf16(o[d][4 * g] * rn * gv[0], o[d][4 * g + 1] * rn * gv[1]); w.y = pk_bf16(o[d][4 * g + 2] * rn * gv[2], o[d][4 * g + 3] * rn * gv[3]);
;                     *(u32x2*)(MIX + orow + 512 + 128 * h + 32 * d + 8 * g + 4 * hi) = w; }
	v_cvt_pk_bf16_f32 v176, v0, v2
	v_mul_f32_e32 v0, v64, v12
	v_mul_f32_e32 v3, v3, v5
	v_mul_f32_e32 v0, v0, v4
	v_cvt_pk_bf16_f32 v177, v0, v3
	v_mov_b32_e32 v2, v100
	v_mov_b32_e32 v3, v101
	v_mov_b32_e32 v4, v102
	v_mov_b32_e32 v5, v103
	v_mul_f32_e32 v0, v37, v12
	v_mul_f32_e32 v0, v0, v2
	v_mul_f32_e32 v2, v35, v12
	v_mul_f32_e32 v2, v2, v3
	v_mul_f32_e32 v3, v65, v12
	v_cvt_pk_bf16_f32 v178, v0, v2
	v_mul_f32_e32 v0, v69, v12
	v_mul_f32_e32 v3, v3, v5
	v_mul_f32_e32 v0, v0, v4
	v_cvt_pk_bf16_f32 v179, v0, v3
	s_nop 1
	v_permlane32_swap_b32_e32 v176, v178
	v_permlane32_swap_b32_e32 v177, v179
	global_store_dwordx4 v[10:11], v[176:179], off offset:1088
	v_mov_b32_e32 v2, v104
	v_mov_b32_e32 v3, v105
	v_mov_b32_e32 v4, v106
	v_mov_b32_e32 v5, v107
	v_mul_f32_e32 v0, v39, v12
	v_mul_f32_e32 v0, v0, v2
	v_mul_f32_e32 v2, v38, v12
	v_mul_f32_e32 v2, v2, v3
	v_mul_f32_e32 v3, v41, v12
	v_cvt_pk_bf16_f32 v176, v0, v2
	v_mul_f32_e32 v0, v43, v12
	v_mul_f32_e32 v3, v3, v5
	v_mul_f32_e32 v0, v0, v4
	v_cvt_pk_bf16_f32 v177, v0, v3
	v_mov_b32_e32 v2, v108
	v_mov_b32_e32 v3, v109
	v_mov_b32_e32 v4, v110
	v_mov_b32_e32 v5, v111
	v_mul_f32_e32 v0, v42, v12
	v_mul_f32_e32 v0, v0, v2
	v_mul_f32_e32 v2, v40, v12
	v_mul_f32_e32 v2, v2, v3
	v_mul_f32_e32 v3, v45, v12
	v_cvt_pk_bf16_f32 v178, v0, v2
	v_mul_f32_e32 v0, v47, v12
	v_mul_f32_e32 v3, v3, v5
	v_mul_f32_e32 v0, v0, v4
	v_cvt_pk_bf16_f32 v179, v0, v3
	s_nop 1
	v_permlane32_swap_b32_e32 v176, v178
	v_permlane32_swap_b32_e32 v177, v179
	global_store_dwordx4 v[10:11], v[176:179], off offset:1120
	v_mov_b32_e32 v2, v112
	v_mov_b32_e32 v3, v113
	v_mov_b32_e32 v4, v114
	v_mov_b32_e32 v5, v115
	v_mul_f32_e32 v0, v44, v12
	v_mul_f32_e32 v0, v0, v2
	v_mul_f32_e32 v2, v18, v12
	v_mul_f32_e32 v2, v2, v3
	v_mul_f32_e32 v3, v20, v12
	v_cvt_pk_bf16_f32 v176, v0, v2
	v_mul_f32_e32 v0, v46, v12
	v_mul_f32_e32 v3, v3, v5
	v_mul_f32_e32 v0, v0, v4
	v_cvt_pk_bf16_f32 v177, v0, v3
	v_mov_b32_e32 v2, v116
	v_mov_b32_e32 v3, v117
	v_mov_b32_e32 v4, v118
	v_mov_b32_e32 v5, v119
	v_mul_f32_e32 v0, v21, v12
	v_mul_f32_e32 v0, v0, v2
	v_mul_f32_e32 v2, v19, v12
	v_mul_f32_e32 v2, v2, v3
	v_mul_f32_e32 v3, v48, v12
	v_cvt_pk_bf16_f32 v178, v0, v2
	v_mul_f32_e32 v0, v49, v12
	v_mul_f32_e32 v3, v3, v5
	v_mul_f32_e32 v0, v0, v4
	v_cvt_pk_bf16_f32 v179, v0, v3
	s_nop 1
	v_permlane32_swap_b32_e32 v176, v178
	v_permlane32_swap_b32_e32 v177, v179
	global_store_dwordx4 v[10:11], v[176:179], off offset:1152
	v_mov_b32_e32 v2, v152
	v_mov_b32_e32 v3, v153
	v_mov_b32_e32 v4, v154
	v_mov_b32_e32 v5, v155
	v_mul_f32_e32 v0, v23, v12
	v_mul_f32_e32 v0, v0, v2
	v_mul_f32_e32 v2, v22, v12
	v_mul_f32_e32 v2, v2, v3
	v_mul_f32_e32 v3, v25, v12
	v_cvt_pk_bf16_f32 v176, v0, v2
	v_mul_f32_e32 v0, v28, v12
	v_mul_f32_e32 v3, v3, v5
	v_mul_f32_e32 v0, v0, v4
	v_cvt_pk_bf16_f32 v177, v0, v3
	v_mov_b32_e32 v2, v156
	v_mov_b32_e32 v3, v157
	v_mov_b32_e32 v4, v158
	v_mov_b32_e32 v5, v159
	v_mul_f32_e32 v0, v26, v12
	v_mul_f32_e32 v0, v0, v2
	v_mul_f32_e32 v2, v24, v12
	v_mul_f32_e32 v2, v2, v3
	v_mul_f32_e32 v3, v74, v12
	v_cvt_pk_bf16_f32 v178, v0, v2
	v_mul_f32_e32 v0, v76, v12
	v_mul_f32_e32 v3, v3, v5
	v_mul_f32_e32 v0, v0, v4
	v_cvt_pk_bf16_f32 v179, v0, v3
	s_nop 1
	v_permlane32_swap_b32_e32 v176, v178
	v_permlane32_swap_b32_e32 v177, v179
	global_store_dwordx4 v[10:11], v[176:179], off offset:1184
	v_mov_b32_e32 v2, v160
	v_mov_b32_e32 v3, v161
	v_mov_b32_e32 v4, v162
	v_mov_b32_e32 v5, v163
	v_mul_f32_e32 v0, v32, v12
	v_mul_f32_e32 v0, v0, v2
	v_mul_f32_e32 v2, v31, v12
	v_mul_f32_e32 v2, v2, v3
	v_mul_f32_e32 v3, v72, v12
	v_cvt_pk_bf16_f32 v176, v0, v2
	v_mul_f32_e32 v0, v75, v12
	v_mul_f32_e32 v3, v3, v5
	v_mul_f32_e32 v0, v0, v4
	v_cvt_pk_bf16_f32 v177, v0, v3
	v_mov_b32_e32 v2, v164
	v_mov_b32_e32 v3, v165
	v_mov_b32_e32 v4, v166
	v_mov_b32_e32 v5, v167
	v_mul_f32_e32 v0, v73, v12
	v_mul_f32_e32 v0, v0, v2
	v_mul_f32_e32 v2, v70, v12
	v_mul_f32_e32 v2, v2, v3
	v_mul_f32_e32 v3, v33, v12
	v_cvt_pk_bf16_f32 v178, v0, v2
	v_mul_f32_e32 v0, v71, v12
	v_mul_f32_e32 v3, v3, v5
	v_mul_f32_e32 v0, v0, v4
	v_cvt_pk_bf16_f32 v179, v0, v3
	s_nop 1
	v_permlane32_swap_b32_e32 v176, v178
	v_permlane32_swap_b32_e32 v177, v179
	global_store_dwordx4 v[10:11], v[176:179], off offset:1216
	v_mov_b32_e32 v2, v168
	v_mov_b32_e32 v3, v169
	v_mov_b32_e32 v4, v170
	v_mov_b32_e32 v5, v171
	v_mul_f32_e32 v0, v30, v12
	v_mul_f32_e32 v0, v0, v2
	v_mul_f32_e32 v2, v29, v12
	v_mul_f32_e32 v2, v2, v3
	v_mul_f32_e32 v3, v13, v12
	v_cvt_pk_bf16_f32 v176, v0, v2
	v_mul_f32_e32 v0, v27, v12
	v_mul_f32_e32 v3, v3, v5
	v_mul_f32_e32 v0, v0, v4
	v_cvt_pk_bf16_f32 v177, v0, v3
	v_mov_b32_e32 v2, v172
	v_mov_b32_e32 v3, v173
	v_mov_b32_e32 v4, v174
	v_mov_b32_e32 v5, v175
	v_mul_f32_e32 v0, v8, v12
	v_mul_f32_e32 v0, v0, v2
	v_mul_f32_e32 v2, v9, v12
	v_mul_f32_e32 v2, v2, v3
	v_mul_f32_e32 v3, v7, v12
	v_cvt_pk_bf16_f32 v178, v0, v2
	v_mul_f32_e32 v0, v6, v12
	v_mul_f32_e32 v3, v3, v5
	v_mul_f32_e32 v0, v0, v4
	v_cvt_pk_bf16_f32 v179, v0, v3
	s_nop 1
	v_permlane32_swap_b32_e32 v176, v178
	v_permlane32_swap_b32_e32 v177, v179
	global_store_dwordx4 v[10:11], v[176:179], off offset:1248
	s_branch .LBB0_175
